# mixer queues 2 and 3: the next-unit ticket atomic returns into a dead VGPR and is waited at its consumer (end of unit) instead of right after issue
# speedup vs baseline: 1.0080x; 1.0060x over previous
.LBB0_351:
	v_mov_b32_e32 v2, s41
	ds_read_b32 v2, v2
	s_waitcnt lgkmcnt(0)
	v_cmp_lt_i32_e64 s[18:19], s33, v2
	v_readfirstlane_b32 s26, v2
	s_and_b64 vcc, exec, s[18:19]
	s_cbranch_vccnz .LBB0_350
	s_and_saveexec_b64 s[20:21], s[48:49]
	s_cbranch_execz .LBB0_356
	s_mov_b64 s[30:31], exec
	v_mbcnt_lo_u32_b32 v2, s30, 0
	v_mbcnt_hi_u32_b32 v2, s31, v2
	v_cmp_eq_u32_e32 vcc, 0, v2
	s_and_saveexec_b64 s[22:23], vcc
	s_cbranch_execz .LBB0_355
	s_bcnt1_i32_b64 s30, s[30:31]
	v_mov_b32_e32 v3, s30
	global_atomic_add v218, v82, v3, s[24:25] sc0
.LBB0_355:
	s_or_b64 exec, exec, s[22:23]
	s_nop 0

.LBB0_374:
	s_waitcnt lgkmcnt(0)
	s_barrier
	s_and_saveexec_b64 s[20:21], s[48:49]
	s_cbranch_execz .LBB0_349
	v_mov_b32_e32 v2, s41
	s_waitcnt vmcnt(0)
	ds_write_b32 v2, v218
	s_branch .LBB0_349

.LBB0_383:
	ds_read_b32 v2, v83
	s_waitcnt lgkmcnt(0)
	v_cmp_lt_i32_e64 s[46:47], s52, v2
	v_readfirstlane_b32 s76, v2
	s_and_b64 vcc, exec, s[46:47]
	s_cbranch_vccnz .LBB0_382
	s_and_saveexec_b64 s[70:71], s[4:5]
	s_cbranch_execz .LBB0_388
	s_mov_b64 s[74:75], exec
	v_mbcnt_lo_u32_b32 v2, s74, 0
	v_mbcnt_hi_u32_b32 v2, s75, v2
	v_cmp_eq_u32_e32 vcc, 0, v2
	s_and_saveexec_b64 s[72:73], vcc
	s_cbranch_execz .LBB0_387
	s_bcnt1_i32_b64 s66, s[74:75]
	v_mov_b32_e32 v3, s66
	global_atomic_add v180, v85, v3, s[60:61] sc0
.LBB0_387:
	s_or_b64 exec, exec, s[72:73]
	s_nop 0

.LBB0_432:
	s_or_b64 exec, exec, s[72:73]
	s_waitcnt lgkmcnt(0)
	s_barrier
	s_and_saveexec_b64 s[70:71], s[4:5]
	s_cbranch_execz .LBB0_381
	v_mov_b32_e32 v2, s33
	s_waitcnt vmcnt(0)
	ds_write_b32 v2, v180
	s_branch .LBB0_381
